# sample-attn QK rows 1-2: 12-slot ring of pipelined ds_read_b128 with counted lgkmcnt instead of serial read+wait(0)
# baseline (speedup 1.0000x reference)
.LBB0_754:
	s_or_b64 exec, exec, s[10:11]
	s_bitset1_b32 s4, 14
	s_ashr_i32 s10, s16, 6
	s_mul_i32 s12, s4, 0x600
	s_mul_hi_u32 s11, s4, 0x600
	s_add_u32 s12, s26, s12
	s_addc_u32 s13, s27, s11
	v_lshl_add_u64 v[0:1], v[8:9], 1, s[12:13]
	s_mov_b32 s11, 0x6a80000
	v_add_co_u32_e32 v0, vcc, s11, v0
	v_readlane_b32 s17, v255, 53
	s_nop 0
	v_addc_co_u32_e32 v1, vcc, 0, v1, vcc
	v_lshl_add_u32 v1, v8, 2, s17
	s_add_i32 s11, s10, 1
	v_and_b32_e32 v64, 63, v8
	v_mov_b32_e32 v0, v209
	v_lshlrev_b32_e32 v0, 16, v0
	ds_write_b32 v1, v0
	v_cvt_f32_i32_e32 v0, s11
	s_mov_b32 s11, 0x42fc0000
	s_waitcnt lgkmcnt(0)
	s_barrier
	v_cmp_lt_f32_e32 vcc, s11, v0
	s_and_b64 s[12:13], vcc, exec
	s_cselect_b32 s11, 0xffffffc0, 0
	v_cndmask_b32_e32 v1, 0, v242, vcc
	s_add_i32 s12, s10, s58
	v_sub_f32_e32 v0, v1, v0
	s_ashr_i32 s13, s12, 31
	v_exp_f32_e32 v0, v0
	s_lshl_b64 s[12:13], s[12:13], 2
	s_add_u32 s12, s22, s12
	s_addc_u32 s13, s23, s13
	global_load_dword v65, v175, s[12:13]
	s_and_b32 s12, s16, 0xffffff00
	s_and_b32 s24, s16, 0xffffffc0
	v_ldexp_f32 v0, v0, s11
	s_add_i32 s11, s12, 0
	s_lshl_b32 s13, s24, 2
	s_add_i32 s13, s17, s13
	v_mul_f32_e32 v66, 0x3fb8aa3b, v0
	v_mov_b32_e32 v0, s11
	v_mad_u32_u24 v67, v64, s72, v0
	v_mov_b32_e32 v44, s13
	ds_read_b128 v[12:15], v67
	ds_read_b128 v[16:19], v67 offset:16
	ds_read_b128 v[20:23], v67 offset:32
	ds_read_b128 v[24:27], v67 offset:48
	ds_read_b128 v[28:31], v44
	ds_read_b128 v[8:11], v44 offset:16
	ds_read_b128 v[4:7], v44 offset:32
	ds_read_b128 v[0:3], v44 offset:48
	s_add_i32 s13, s11, 0x10800
	s_waitcnt lgkmcnt(3)
	v_mul_f32_e32 v13, v13, v29
	v_fmac_f32_e32 v13, v12, v28
	v_mul_f32_e32 v12, v15, v31
	v_fmac_f32_e32 v12, v14, v30
	v_add_f32_e32 v12, v13, v12
	s_waitcnt lgkmcnt(2)
	v_mul_f32_e32 v13, v17, v9
	v_mul_f32_e32 v14, v19, v11
	v_fmac_f32_e32 v13, v16, v8
	v_fmac_f32_e32 v14, v18, v10
	v_add_f32_e32 v12, 0, v12
	v_add_f32_e32 v13, v13, v14
	v_add_f32_e32 v12, v12, v13
	s_waitcnt lgkmcnt(1)
	v_mul_f32_e32 v13, v21, v5
	v_mul_f32_e32 v14, v23, v7
	v_fmac_f32_e32 v13, v20, v4
	v_fmac_f32_e32 v14, v22, v6
	v_add_f32_e32 v13, v13, v14
	v_add_f32_e32 v12, v12, v13
	s_waitcnt lgkmcnt(0)
	v_mul_f32_e32 v13, v25, v1
	v_mul_f32_e32 v14, v27, v3
	v_fmac_f32_e32 v13, v24, v0
	v_fmac_f32_e32 v14, v26, v2
	v_add_f32_e32 v13, v13, v14
	v_add_f32_e32 v16, v12, v13
	ds_read_b128 v[12:15], v67 offset:64
	ds_read_b128 v[24:27], v44 offset:64
	v_cmp_eq_u32_e32 vcc, 0, v64
	s_waitcnt lgkmcnt(0)
	v_mul_f32_e32 v13, v13, v25
	v_fmac_f32_e32 v13, v12, v24
	v_mul_f32_e32 v12, v15, v27
	v_fmac_f32_e32 v12, v14, v26
	v_add_f32_e32 v12, v13, v12
	v_add_f32_e32 v20, v16, v12
	ds_read_b128 v[12:15], v67 offset:80
	ds_read_b128 v[16:19], v44 offset:80
	s_waitcnt lgkmcnt(0)
	v_mul_f32_e32 v13, v13, v17
	v_fmac_f32_e32 v13, v12, v16
	v_mul_f32_e32 v12, v15, v19
	v_fmac_f32_e32 v12, v14, v18
	v_add_f32_e32 v12, v13, v12
	v_add_f32_e32 v32, v20, v12
	ds_read_b128 v[12:15], v67 offset:96
	ds_read_b128 v[20:23], v44 offset:96
	s_waitcnt lgkmcnt(0)
	v_mul_f32_e32 v13, v13, v21
	v_fmac_f32_e32 v13, v12, v20
	v_mul_f32_e32 v12, v15, v23
	v_fmac_f32_e32 v12, v14, v22
	v_add_f32_e32 v12, v13, v12
	v_add_f32_e32 v36, v32, v12
	ds_read_b128 v[32:35], v67 offset:112
	ds_read_b128 v[12:15], v44 offset:112
	s_waitcnt lgkmcnt(0)
	v_mul_f32_e32 v33, v33, v13
	v_fmac_f32_e32 v33, v32, v12
	v_mul_f32_e32 v32, v35, v15
	v_fmac_f32_e32 v32, v34, v14
	v_add_f32_e32 v32, v33, v32
	v_add_f32_e32 v36, v36, v32
	ds_read_b128 v[32:35], v67 offset:128
	ds_read_b128 v[48:51], v44 offset:128
	s_waitcnt lgkmcnt(0)
	v_mul_f32_e32 v33, v33, v49
	v_fmac_f32_e32 v33, v32, v48
	v_mul_f32_e32 v32, v35, v51
	v_fmac_f32_e32 v32, v34, v50
	v_add_f32_e32 v32, v33, v32
	v_add_f32_e32 v40, v36, v32
	ds_read_b128 v[36:39], v67 offset:144
	ds_read_b128 v[32:35], v44 offset:144
	s_waitcnt lgkmcnt(0)
	v_mul_f32_e32 v37, v37, v33
	v_fmac_f32_e32 v37, v36, v32
	v_mul_f32_e32 v36, v39, v35
	v_fmac_f32_e32 v36, v38, v34
	v_add_f32_e32 v36, v37, v36
	v_add_f32_e32 v40, v40, v36
	ds_read_b128 v[36:39], v67 offset:160
	ds_read_b128 v[52:55], v44 offset:160
	s_waitcnt lgkmcnt(0)
	v_mul_f32_e32 v37, v37, v53
	v_fmac_f32_e32 v37, v36, v52
	v_mul_f32_e32 v36, v39, v55
	v_fmac_f32_e32 v36, v38, v54
	v_add_f32_e32 v36, v37, v36
	v_add_f32_e32 v45, v40, v36
	ds_read_b128 v[40:43], v67 offset:176
	ds_read_b128 v[36:39], v44 offset:176
	s_waitcnt lgkmcnt(0)
	v_mul_f32_e32 v41, v41, v37
	v_fmac_f32_e32 v41, v40, v36
	v_mul_f32_e32 v40, v43, v39
	v_fmac_f32_e32 v40, v42, v38
	v_add_f32_e32 v40, v41, v40
	v_add_f32_e32 v45, v45, v40
	ds_read_b128 v[40:43], v67 offset:192
	ds_read_b128 v[56:59], v44 offset:192
	s_waitcnt lgkmcnt(0)
	v_mul_f32_e32 v41, v41, v57
	v_fmac_f32_e32 v41, v40, v56
	v_mul_f32_e32 v40, v43, v59
	v_fmac_f32_e32 v40, v42, v58
	v_add_f32_e32 v40, v41, v40
	v_add_f32_e32 v45, v45, v40
	ds_read_b128 v[60:63], v67 offset:208
	ds_read_b128 v[40:43], v44 offset:208
	s_waitcnt lgkmcnt(0)
	v_mul_f32_e32 v46, v61, v41
	v_mul_f32_e32 v47, v63, v43
	v_fmac_f32_e32 v46, v60, v40
	v_fmac_f32_e32 v47, v62, v42
	ds_read_b128 v[68:71], v67 offset:224
	ds_read_b128 v[60:63], v44 offset:224
	v_add_f32_e32 v46, v46, v47
	v_add_f32_e32 v45, v45, v46
	s_waitcnt lgkmcnt(0)
	v_mul_f32_e32 v46, v69, v61
	v_mul_f32_e32 v47, v71, v63
	v_fmac_f32_e32 v46, v68, v60
	v_fmac_f32_e32 v47, v70, v62
	v_add_f32_e32 v46, v46, v47
	v_add_f32_e32 v72, v45, v46
	ds_read_b128 v[68:71], v67 offset:240
	ds_read_b128 v[44:47], v44 offset:240
	s_waitcnt lgkmcnt(0)
	v_mul_f32_e32 v69, v69, v45
	v_fmac_f32_e32 v69, v68, v44
	v_mul_f32_e32 v68, v71, v47
	v_fmac_f32_e32 v68, v70, v46
	v_add_f32_e32 v68, v69, v68
	v_add_f32_e32 v68, v72, v68
	v_sub_u32_e32 v69, 0x80, v64
	v_cvt_f32_ubyte0_e32 v69, v69
	v_fma_f32 v68, -v66, v69, v68
	v_or_b32_e32 v69, 64, v64
	v_sub_u32_e32 v69, 0x80, v69
	v_cvt_f32_ubyte0_e32 v69, v69
	s_add_i32 s13, s11, 0x10800
	v_mov_b32_e32 v184, s13
	ds_read_b128 v[116:119], v67 offset:33792
	ds_read_b128 v[120:123], v67 offset:33808
	ds_read_b128 v[124:127], v67 offset:33824
	ds_read_b128 v[128:131], v67 offset:33840
	ds_read_b128 v[132:135], v67 offset:33856
	ds_read_b128 v[136:139], v67 offset:33872
	ds_read_b128 v[140:143], v67 offset:33888
	ds_read_b128 v[144:147], v67 offset:33904
	ds_read_b128 v[148:151], v67 offset:33920
	ds_read_b128 v[152:155], v67 offset:33936
	ds_read_b128 v[156:159], v67 offset:33952
	ds_read_b128 v[160:163], v67 offset:33968
	s_waitcnt lgkmcnt(11)
	v_mul_f32_e32 v72, v29, v117
	v_fmac_f32_e32 v72, v28, v116
	v_mul_f32_e32 v73, v31, v119
	v_fmac_f32_e32 v73, v30, v118
	v_add_f32_e32 v72, v72, v73
	v_add_f32_e32 v70, 0, v72
	ds_read_b128 v[116:119], v67 offset:33984
	s_waitcnt lgkmcnt(11)
	v_mul_f32_e32 v72, v9, v121
	v_fmac_f32_e32 v72, v8, v120
	v_mul_f32_e32 v73, v11, v123
	v_fmac_f32_e32 v73, v10, v122
	v_add_f32_e32 v72, v72, v73
	v_add_f32_e32 v70, v70, v72
	ds_read_b128 v[120:123], v67 offset:34000
	s_waitcnt lgkmcnt(11)
	v_mul_f32_e32 v72, v5, v125
	v_fmac_f32_e32 v72, v4, v124
	v_mul_f32_e32 v73, v7, v127
	v_fmac_f32_e32 v73, v6, v126
	v_add_f32_e32 v72, v72, v73
	v_add_f32_e32 v70, v70, v72
	ds_read_b128 v[124:127], v67 offset:34016
	s_waitcnt lgkmcnt(11)
	v_mul_f32_e32 v72, v1, v129
	v_fmac_f32_e32 v72, v0, v128
	v_mul_f32_e32 v73, v3, v131
	v_fmac_f32_e32 v73, v2, v130
	v_add_f32_e32 v72, v72, v73
	v_add_f32_e32 v70, v70, v72
	ds_read_b128 v[128:131], v67 offset:34032
	s_waitcnt lgkmcnt(11)
	v_mul_f32_e32 v72, v25, v133
	v_fmac_f32_e32 v72, v24, v132
	v_mul_f32_e32 v73, v27, v135
	v_fmac_f32_e32 v73, v26, v134
	v_add_f32_e32 v72, v72, v73
	v_add_f32_e32 v70, v70, v72
	ds_read_b128 v[132:135], v184
	s_waitcnt lgkmcnt(11)
	v_mul_f32_e32 v72, v17, v137
	v_fmac_f32_e32 v72, v16, v136
	v_mul_f32_e32 v73, v19, v139
	v_fmac_f32_e32 v73, v18, v138
	v_add_f32_e32 v72, v72, v73
	v_add_f32_e32 v70, v70, v72
	ds_read_b128 v[136:139], v184 offset:16
	s_waitcnt lgkmcnt(11)
	v_mul_f32_e32 v72, v21, v141
	v_fmac_f32_e32 v72, v20, v140
	v_mul_f32_e32 v73, v23, v143
	v_fmac_f32_e32 v73, v22, v142
	v_add_f32_e32 v72, v72, v73
	v_add_f32_e32 v70, v70, v72
	ds_read_b128 v[140:143], v184 offset:32
	s_waitcnt lgkmcnt(11)
	v_mul_f32_e32 v72, v13, v145
	v_fmac_f32_e32 v72, v12, v144
	v_mul_f32_e32 v73, v15, v147
	v_fmac_f32_e32 v73, v14, v146
	v_add_f32_e32 v72, v72, v73
	v_add_f32_e32 v70, v70, v72
	ds_read_b128 v[144:147], v184 offset:48
	s_waitcnt lgkmcnt(11)
	v_mul_f32_e32 v72, v49, v149
	v_fmac_f32_e32 v72, v48, v148
	v_mul_f32_e32 v73, v51, v151
	v_fmac_f32_e32 v73, v50, v150
	v_add_f32_e32 v72, v72, v73
	v_add_f32_e32 v70, v70, v72
	ds_read_b128 v[148:151], v184 offset:64
	s_waitcnt lgkmcnt(11)
	v_mul_f32_e32 v72, v33, v153
	v_fmac_f32_e32 v72, v32, v152
	v_mul_f32_e32 v73, v35, v155
	v_fmac_f32_e32 v73, v34, v154
	v_add_f32_e32 v72, v72, v73
	v_add_f32_e32 v70, v70, v72
	ds_read_b128 v[152:155], v184 offset:80
	s_waitcnt lgkmcnt(11)
	v_mul_f32_e32 v72, v53, v157
	v_fmac_f32_e32 v72, v52, v156
	v_mul_f32_e32 v73, v55, v159
	v_fmac_f32_e32 v73, v54, v158
	v_add_f32_e32 v72, v72, v73
	v_add_f32_e32 v70, v70, v72
	ds_read_b128 v[156:159], v184 offset:96
	s_waitcnt lgkmcnt(11)
	v_mul_f32_e32 v72, v37, v161
	v_fmac_f32_e32 v72, v36, v160
	v_mul_f32_e32 v73, v39, v163
	v_fmac_f32_e32 v73, v38, v162
	v_add_f32_e32 v72, v72, v73
	v_add_f32_e32 v70, v70, v72
	ds_read_b128 v[160:163], v184 offset:112
	s_waitcnt lgkmcnt(11)
	v_mul_f32_e32 v72, v57, v117
	v_fmac_f32_e32 v72, v56, v116
	v_mul_f32_e32 v73, v59, v119
	v_fmac_f32_e32 v73, v58, v118
	v_add_f32_e32 v72, v72, v73
	v_add_f32_e32 v70, v70, v72
	ds_read_b128 v[116:119], v184 offset:128
	s_waitcnt lgkmcnt(11)
	v_mul_f32_e32 v72, v41, v121
	v_fmac_f32_e32 v72, v40, v120
	v_mul_f32_e32 v73, v43, v123
	v_fmac_f32_e32 v73, v42, v122
	v_add_f32_e32 v72, v72, v73
	v_add_f32_e32 v70, v70, v72
	ds_read_b128 v[120:123], v184 offset:144
	s_waitcnt lgkmcnt(11)
	v_mul_f32_e32 v72, v61, v125
	v_fmac_f32_e32 v72, v60, v124
	v_mul_f32_e32 v73, v63, v127
	v_fmac_f32_e32 v73, v62, v126
	v_add_f32_e32 v72, v72, v73
	v_add_f32_e32 v70, v70, v72
	ds_read_b128 v[124:127], v184 offset:160
	s_waitcnt lgkmcnt(11)
	v_mul_f32_e32 v72, v45, v129
	v_fmac_f32_e32 v72, v44, v128
	v_mul_f32_e32 v73, v47, v131
	v_fmac_f32_e32 v73, v46, v130
	v_add_f32_e32 v72, v72, v73
	v_add_f32_e32 v70, v70, v72
	ds_read_b128 v[128:131], v184 offset:176
	s_waitcnt lgkmcnt(11)
	v_mul_f32_e32 v72, v29, v133
	v_fmac_f32_e32 v72, v28, v132
	v_mul_f32_e32 v73, v31, v135
	v_fmac_f32_e32 v73, v30, v134
	v_add_f32_e32 v72, v72, v73
	v_add_f32_e32 v71, 0, v72
	ds_read_b128 v[132:135], v184 offset:192
	s_waitcnt lgkmcnt(11)
	v_mul_f32_e32 v72, v9, v137
	v_fmac_f32_e32 v72, v8, v136
	v_mul_f32_e32 v73, v11, v139
	v_fmac_f32_e32 v73, v10, v138
	v_add_f32_e32 v72, v72, v73
	v_add_f32_e32 v71, v71, v72
	ds_read_b128 v[136:139], v184 offset:208
	s_waitcnt lgkmcnt(11)
	v_mul_f32_e32 v72, v5, v141
	v_fmac_f32_e32 v72, v4, v140
	v_mul_f32_e32 v73, v7, v143
	v_fmac_f32_e32 v73, v6, v142
	v_add_f32_e32 v72, v72, v73
	v_add_f32_e32 v71, v71, v72
	ds_read_b128 v[140:143], v184 offset:224
	s_waitcnt lgkmcnt(11)
	v_mul_f32_e32 v72, v1, v145
	v_fmac_f32_e32 v72, v0, v144
	v_mul_f32_e32 v73, v3, v147
	v_fmac_f32_e32 v73, v2, v146
	v_add_f32_e32 v72, v72, v73
	v_add_f32_e32 v71, v71, v72
	ds_read_b128 v[144:147], v184 offset:240
	s_waitcnt lgkmcnt(11)
	v_mul_f32_e32 v72, v25, v149
	v_fmac_f32_e32 v72, v24, v148
	v_mul_f32_e32 v73, v27, v151
	v_fmac_f32_e32 v73, v26, v150
	v_add_f32_e32 v72, v72, v73
	v_add_f32_e32 v71, v71, v72
	s_waitcnt lgkmcnt(10)
	v_mul_f32_e32 v72, v17, v153
	v_fmac_f32_e32 v72, v16, v152
	v_mul_f32_e32 v73, v19, v155
	v_fmac_f32_e32 v73, v18, v154
	v_add_f32_e32 v72, v72, v73
	v_add_f32_e32 v71, v71, v72
	s_waitcnt lgkmcnt(9)
	v_mul_f32_e32 v72, v21, v157
	v_fmac_f32_e32 v72, v20, v156
	v_mul_f32_e32 v73, v23, v159
	v_fmac_f32_e32 v73, v22, v158
	v_add_f32_e32 v72, v72, v73
	v_add_f32_e32 v71, v71, v72
	s_waitcnt lgkmcnt(8)
	v_mul_f32_e32 v72, v13, v161
	v_fmac_f32_e32 v72, v12, v160
	v_mul_f32_e32 v73, v15, v163
	v_fmac_f32_e32 v73, v14, v162
	v_add_f32_e32 v72, v72, v73
	v_add_f32_e32 v71, v71, v72
	s_waitcnt lgkmcnt(7)
	v_mul_f32_e32 v72, v49, v117
	v_fmac_f32_e32 v72, v48, v116
	v_mul_f32_e32 v73, v51, v119
	v_fmac_f32_e32 v73, v50, v118
	v_add_f32_e32 v72, v72, v73
	v_add_f32_e32 v71, v71, v72
	s_waitcnt lgkmcnt(6)
	v_mul_f32_e32 v72, v33, v121
	v_fmac_f32_e32 v72, v32, v120
	v_mul_f32_e32 v73, v35, v123
	v_fmac_f32_e32 v73, v34, v122
	v_add_f32_e32 v72, v72, v73
	v_add_f32_e32 v71, v71, v72
	s_waitcnt lgkmcnt(5)
	v_mul_f32_e32 v72, v53, v125
	v_fmac_f32_e32 v72, v52, v124
	v_mul_f32_e32 v73, v55, v127
	v_fmac_f32_e32 v73, v54, v126
	v_add_f32_e32 v72, v72, v73
	v_add_f32_e32 v71, v71, v72
	s_waitcnt lgkmcnt(4)
	v_mul_f32_e32 v72, v37, v129
	v_fmac_f32_e32 v72, v36, v128
	v_mul_f32_e32 v73, v39, v131
	v_fmac_f32_e32 v73, v38, v130
	v_add_f32_e32 v72, v72, v73
	v_add_f32_e32 v71, v71, v72
	s_waitcnt lgkmcnt(3)
	v_mul_f32_e32 v72, v57, v133
	v_fmac_f32_e32 v72, v56, v132
	v_mul_f32_e32 v73, v59, v135
	v_fmac_f32_e32 v73, v58, v134
	v_add_f32_e32 v72, v72, v73
	v_add_f32_e32 v71, v71, v72
	s_waitcnt lgkmcnt(2)
	v_mul_f32_e32 v72, v41, v137
	v_fmac_f32_e32 v72, v40, v136
	v_mul_f32_e32 v73, v43, v139
	v_fmac_f32_e32 v73, v42, v138
	v_add_f32_e32 v72, v72, v73
	v_add_f32_e32 v71, v71, v72
	s_waitcnt lgkmcnt(1)
	v_mul_f32_e32 v72, v61, v141
	v_fmac_f32_e32 v72, v60, v140
	v_mul_f32_e32 v73, v63, v143
	v_fmac_f32_e32 v73, v62, v142
	v_add_f32_e32 v72, v72, v73
	v_add_f32_e32 v71, v71, v72
	s_waitcnt lgkmcnt(0)
	v_mul_f32_e32 v72, v45, v145
	v_fmac_f32_e32 v72, v44, v144
	v_mul_f32_e32 v73, v47, v147
	v_fmac_f32_e32 v73, v46, v146
	v_add_f32_e32 v72, v72, v73
	v_add_f32_e32 v71, v71, v72
	v_fma_f32 v67, -v66, v69, v70
	s_mul_i32 s13, s10, 0x210
	s_add_i32 s16, s13, 0
	s_add_i32 s16, s16, 0x21420
	v_mov_b32_e32 v0, v71
	v_and_b32_e32 v3, 64, v237
	v_fmac_f32_e32 v0, 0x80000000, v66
	v_add_u32_e32 v3, 64, v3
	v_xor_b32_e32 v4, 1, v237
	v_cndmask_b32_e32 v2, v243, v0, vcc
	s_waitcnt vmcnt(0)
	v_mul_f32_e32 v0, 0x3fb8aa3b, v65
	v_cmp_lt_i32_e64 s[22:23], v4, v3
	v_max_f32_e32 v1, v2, v0
	v_max3_f32 v1, v68, v67, v1
	v_cndmask_b32_e64 v4, v237, v4, s[22:23]
	v_lshlrev_b32_e32 v5, 2, v4
	ds_bpermute_b32 v4, v5, v1
	s_waitcnt lgkmcnt(0)
	v_max_f32_e32 v4, v4, v4
	v_max_f32_e32 v1, v1, v4
	v_xor_b32_e32 v4, 2, v237
	v_cmp_lt_i32_e64 s[22:23], v4, v3
	s_nop 1
	v_cndmask_b32_e64 v4, v237, v4, s[22:23]
	v_lshlrev_b32_e32 v6, 2, v4
	ds_bpermute_b32 v4, v6, v1
	s_waitcnt lgkmcnt(0)
	v_max_f32_e32 v4, v4, v4
	v_max_f32_e32 v1, v1, v4
	v_xor_b32_e32 v4, 4, v237
	v_cmp_lt_i32_e64 s[22:23], v4, v3
	s_nop 1
	v_cndmask_b32_e64 v4, v237, v4, s[22:23]
	v_lshlrev_b32_e32 v7, 2, v4
	ds_bpermute_b32 v4, v7, v1
	s_waitcnt lgkmcnt(0)
	v_max_f32_e32 v4, v4, v4
	v_max_f32_e32 v1, v1, v4
	v_xor_b32_e32 v4, 8, v237
	v_cmp_lt_i32_e64 s[22:23], v4, v3
	s_nop 1
	v_cndmask_b32_e64 v4, v237, v4, s[22:23]
	v_lshlrev_b32_e32 v8, 2, v4
	ds_bpermute_b32 v4, v8, v1
	s_waitcnt lgkmcnt(0)
	v_max_f32_e32 v4, v4, v4
	v_max_f32_e32 v1, v1, v4
	v_xor_b32_e32 v4, 16, v237
	v_cmp_lt_i32_e64 s[22:23], v4, v3
	s_nop 1
	v_cndmask_b32_e64 v4, v237, v4, s[22:23]
	v_lshlrev_b32_e32 v9, 2, v4
	ds_bpermute_b32 v4, v9, v1
	s_waitcnt lgkmcnt(0)
	v_max_f32_e32 v4, v4, v4
	v_max_f32_e32 v1, v1, v4
	v_xor_b32_e32 v4, 32, v237
	v_cmp_lt_i32_e64 s[22:23], v4, v3
	s_nop 1
	v_cndmask_b32_e64 v3, v237, v4, s[22:23]
	v_lshlrev_b32_e32 v3, 2, v3
	ds_bpermute_b32 v4, v3, v1
	s_waitcnt lgkmcnt(0)
	v_max_f32_e32 v4, v4, v4
	v_max_f32_e32 v1, v1, v4
	v_sub_f32_e32 v4, v68, v1
	v_exp_f32_e32 v10, v4
	v_sub_f32_e32 v11, v67, v1
	v_exp_f32_e32 v11, v11
	v_sub_f32_e32 v2, v2, v1
	v_add_f32_e32 v4, 0, v10
	v_add_f32_e32 v12, v11, v4
	v_exp_f32_e32 v4, v2
	s_nop 0
	v_add_f32_e32 v2, v4, v12
	ds_bpermute_b32 v5, v5, v2
	s_waitcnt lgkmcnt(0)
	v_add_f32_e32 v2, v2, v5
	ds_bpermute_b32 v5, v6, v2
	s_waitcnt lgkmcnt(0)
	v_add_f32_e32 v2, v2, v5
	ds_bpermute_b32 v5, v7, v2
	s_waitcnt lgkmcnt(0)
	v_add_f32_e32 v2, v2, v5
	ds_bpermute_b32 v5, v8, v2
	s_waitcnt lgkmcnt(0)
	v_add_f32_e32 v2, v2, v5
	ds_bpermute_b32 v5, v9, v2
	s_waitcnt lgkmcnt(0)
	v_add_f32_e32 v2, v2, v5
	ds_bpermute_b32 v3, v3, v2
	v_lshl_add_u32 v5, v64, 2, s16
	ds_write2st64_b32 v5, v10, v11 offset1:1
	s_and_saveexec_b64 s[10:11], vcc
	v_mov_b32_e32 v5, s16
	ds_write_b32 v5, v4 offset:512
	s_or_b64 exec, exec, s[10:11]
	s_waitcnt lgkmcnt(0)
	s_add_i32 s10, s12, 0x10a10
	v_lshlrev_b32_e32 v149, 2, v64
	v_add_u32_e32 v149, s10, v149
	v_add_u32_e32 v150, 0x400, v149
	v_add_u32_e32 v151, 0x800, v149
	v_add_u32_e32 v152, 0xc00, v149
	s_add_i32 s11, s13, 0x21420
	v_mov_b32_e32 v148, s11
	v_mov_b32_e32 v4, 0
	ds_read_b128 v[116:119], v148
	ds_read_b128 v[120:123], v148 offset:16
	ds_read2_b32 v[124:125], v149 offset1:132
	ds_read2_b32 v[126:127], v150 offset0:8 offset1:140
	ds_read2_b32 v[128:129], v151 offset0:16 offset1:148
	ds_read2_b32 v[130:131], v152 offset0:24 offset1:156
	v_add_u32_e32 v149, 0x1080, v149
	v_add_u32_e32 v150, 0x1080, v150
	v_add_u32_e32 v151, 0x1080, v151
	v_add_u32_e32 v152, 0x1080, v152
	ds_read_b128 v[132:135], v148 offset:32
	ds_read_b128 v[136:139], v148 offset:48
	ds_read2_b32 v[140:141], v149 offset1:132
	ds_read2_b32 v[142:143], v150 offset0:8 offset1:140
	ds_read2_b32 v[144:145], v151 offset0:16 offset1:148
	ds_read2_b32 v[146:147], v152 offset0:24 offset1:156
	v_add_u32_e32 v149, 0x1080, v149
	v_add_u32_e32 v150, 0x1080, v150
	v_add_u32_e32 v151, 0x1080, v151
	v_add_u32_e32 v152, 0x1080, v152
	s_waitcnt lgkmcnt(6)
	v_fmac_f32_e32 v4, v116, v124
	v_fmac_f32_e32 v4, v117, v125
	v_fmac_f32_e32 v4, v118, v126
	v_fmac_f32_e32 v4, v119, v127
	v_fmac_f32_e32 v4, v120, v128
	v_fmac_f32_e32 v4, v121, v129
	v_fmac_f32_e32 v4, v122, v130
	v_fmac_f32_e32 v4, v123, v131
	ds_read_b128 v[116:119], v148 offset:64
	ds_read_b128 v[120:123], v148 offset:80
	ds_read2_b32 v[124:125], v149 offset1:132
	ds_read2_b32 v[126:127], v150 offset0:8 offset1:140
	ds_read2_b32 v[128:129], v151 offset0:16 offset1:148
	ds_read2_b32 v[130:131], v152 offset0:24 offset1:156
	v_add_u32_e32 v149, 0x1080, v149
	v_add_u32_e32 v150, 0x1080, v150
	v_add_u32_e32 v151, 0x1080, v151
	v_add_u32_e32 v152, 0x1080, v152
	s_waitcnt lgkmcnt(6)
	v_fmac_f32_e32 v4, v132, v140
	v_fmac_f32_e32 v4, v133, v141
	v_fmac_f32_e32 v4, v134, v142
	v_fmac_f32_e32 v4, v135, v143
	v_fmac_f32_e32 v4, v136, v144
	v_fmac_f32_e32 v4, v137, v145
	v_fmac_f32_e32 v4, v138, v146
	v_fmac_f32_e32 v4, v139, v147
	ds_read_b128 v[132:135], v148 offset:96
	ds_read_b128 v[136:139], v148 offset:112
	ds_read2_b32 v[140:141], v149 offset1:132
	ds_read2_b32 v[142:143], v150 offset0:8 offset1:140
	ds_read2_b32 v[144:145], v151 offset0:16 offset1:148
	ds_read2_b32 v[146:147], v152 offset0:24 offset1:156
	v_add_u32_e32 v149, 0x1080, v149
	v_add_u32_e32 v150, 0x1080, v150
	v_add_u32_e32 v151, 0x1080, v151
	v_add_u32_e32 v152, 0x1080, v152
	s_waitcnt lgkmcnt(6)
	v_fmac_f32_e32 v4, v116, v124
	v_fmac_f32_e32 v4, v117, v125
	v_fmac_f32_e32 v4, v118, v126
	v_fmac_f32_e32 v4, v119, v127
	v_fmac_f32_e32 v4, v120, v128
	v_fmac_f32_e32 v4, v121, v129
	v_fmac_f32_e32 v4, v122, v130
	v_fmac_f32_e32 v4, v123, v131
	ds_read_b128 v[116:119], v148 offset:128
	ds_read_b128 v[120:123], v148 offset:144
	ds_read2_b32 v[124:125], v149 offset1:132
	ds_read2_b32 v[126:127], v150 offset0:8 offset1:140
	ds_read2_b32 v[128:129], v151 offset0:16 offset1:148
	ds_read2_b32 v[130:131], v152 offset0:24 offset1:156
	v_add_u32_e32 v149, 0x1080, v149
	v_add_u32_e32 v150, 0x1080, v150
	v_add_u32_e32 v151, 0x1080, v151
	v_add_u32_e32 v152, 0x1080, v152
	s_waitcnt lgkmcnt(6)
	v_fmac_f32_e32 v4, v132, v140
	v_fmac_f32_e32 v4, v133, v141
	v_fmac_f32_e32 v4, v134, v142
	v_fmac_f32_e32 v4, v135, v143
	v_fmac_f32_e32 v4, v136, v144
	v_fmac_f32_e32 v4, v137, v145
	v_fmac_f32_e32 v4, v138, v146
	v_fmac_f32_e32 v4, v139, v147
	ds_read_b128 v[132:135], v148 offset:160
	ds_read_b128 v[136:139], v148 offset:176
	ds_read2_b32 v[140:141], v149 offset1:132
	ds_read2_b32 v[142:143], v150 offset0:8 offset1:140
	ds_read2_b32 v[144:145], v151 offset0:16 offset1:148
	ds_read2_b32 v[146:147], v152 offset0:24 offset1:156
	v_add_u32_e32 v149, 0x1080, v149
	v_add_u32_e32 v150, 0x1080, v150
	v_add_u32_e32 v151, 0x1080, v151
	v_add_u32_e32 v152, 0x1080, v152
	s_waitcnt lgkmcnt(6)
	v_fmac_f32_e32 v4, v116, v124
	v_fmac_f32_e32 v4, v117, v125
	v_fmac_f32_e32 v4, v118, v126
	v_fmac_f32_e32 v4, v119, v127
	v_fmac_f32_e32 v4, v120, v128
	v_fmac_f32_e32 v4, v121, v129
	v_fmac_f32_e32 v4, v122, v130
	v_fmac_f32_e32 v4, v123, v131
	ds_read_b128 v[116:119], v148 offset:192
	ds_read_b128 v[120:123], v148 offset:208
	ds_read2_b32 v[124:125], v149 offset1:132
	ds_read2_b32 v[126:127], v150 offset0:8 offset1:140
	ds_read2_b32 v[128:129], v151 offset0:16 offset1:148
	ds_read2_b32 v[130:131], v152 offset0:24 offset1:156
	v_add_u32_e32 v149, 0x1080, v149
	v_add_u32_e32 v150, 0x1080, v150
	v_add_u32_e32 v151, 0x1080, v151
	v_add_u32_e32 v152, 0x1080, v152
	s_waitcnt lgkmcnt(6)
	v_fmac_f32_e32 v4, v132, v140
	v_fmac_f32_e32 v4, v133, v141
	v_fmac_f32_e32 v4, v134, v142
	v_fmac_f32_e32 v4, v135, v143
	v_fmac_f32_e32 v4, v136, v144
	v_fmac_f32_e32 v4, v137, v145
	v_fmac_f32_e32 v4, v138, v146
	v_fmac_f32_e32 v4, v139, v147
	ds_read_b128 v[132:135], v148 offset:224
	ds_read_b128 v[136:139], v148 offset:240
	ds_read2_b32 v[140:141], v149 offset1:132
	ds_read2_b32 v[142:143], v150 offset0:8 offset1:140
	ds_read2_b32 v[144:145], v151 offset0:16 offset1:148
	ds_read2_b32 v[146:147], v152 offset0:24 offset1:156
	v_add_u32_e32 v149, 0x1080, v149
	v_add_u32_e32 v150, 0x1080, v150
	v_add_u32_e32 v151, 0x1080, v151
	v_add_u32_e32 v152, 0x1080, v152
	s_waitcnt lgkmcnt(6)
	v_fmac_f32_e32 v4, v116, v124
	v_fmac_f32_e32 v4, v117, v125
	v_fmac_f32_e32 v4, v118, v126
	v_fmac_f32_e32 v4, v119, v127
	v_fmac_f32_e32 v4, v120, v128
	v_fmac_f32_e32 v4, v121, v129
	v_fmac_f32_e32 v4, v122, v130
	v_fmac_f32_e32 v4, v123, v131
	ds_read_b128 v[116:119], v148 offset:256
	ds_read_b128 v[120:123], v148 offset:272
	ds_read2_b32 v[124:125], v149 offset1:132
	ds_read2_b32 v[126:127], v150 offset0:8 offset1:140
	ds_read2_b32 v[128:129], v151 offset0:16 offset1:148
	ds_read2_b32 v[130:131], v152 offset0:24 offset1:156
	v_add_u32_e32 v149, 0x1080, v149
	v_add_u32_e32 v150, 0x1080, v150
	v_add_u32_e32 v151, 0x1080, v151
	v_add_u32_e32 v152, 0x1080, v152
	s_waitcnt lgkmcnt(6)
	v_fmac_f32_e32 v4, v132, v140
	v_fmac_f32_e32 v4, v133, v141
	v_fmac_f32_e32 v4, v134, v142
	v_fmac_f32_e32 v4, v135, v143
	v_fmac_f32_e32 v4, v136, v144
	v_fmac_f32_e32 v4, v137, v145
	v_fmac_f32_e32 v4, v138, v146
	v_fmac_f32_e32 v4, v139, v147
	ds_read_b128 v[132:135], v148 offset:288
	ds_read_b128 v[136:139], v148 offset:304
	ds_read2_b32 v[140:141], v149 offset1:132
	ds_read2_b32 v[142:143], v150 offset0:8 offset1:140
	ds_read2_b32 v[144:145], v151 offset0:16 offset1:148
	ds_read2_b32 v[146:147], v152 offset0:24 offset1:156
	v_add_u32_e32 v149, 0x1080, v149
	v_add_u32_e32 v150, 0x1080, v150
	v_add_u32_e32 v151, 0x1080, v151
	v_add_u32_e32 v152, 0x1080, v152
	s_waitcnt lgkmcnt(6)
	v_fmac_f32_e32 v4, v116, v124
	v_fmac_f32_e32 v4, v117, v125
	v_fmac_f32_e32 v4, v118, v126
	v_fmac_f32_e32 v4, v119, v127
	v_fmac_f32_e32 v4, v120, v128
	v_fmac_f32_e32 v4, v121, v129
	v_fmac_f32_e32 v4, v122, v130
	v_fmac_f32_e32 v4, v123, v131
	ds_read_b128 v[116:119], v148 offset:320
	ds_read_b128 v[120:123], v148 offset:336
	ds_read2_b32 v[124:125], v149 offset1:132
	ds_read2_b32 v[126:127], v150 offset0:8 offset1:140
	ds_read2_b32 v[128:129], v151 offset0:16 offset1:148
	ds_read2_b32 v[130:131], v152 offset0:24 offset1:156
	v_add_u32_e32 v149, 0x1080, v149
	v_add_u32_e32 v150, 0x1080, v150
	v_add_u32_e32 v151, 0x1080, v151
	v_add_u32_e32 v152, 0x1080, v152
	s_waitcnt lgkmcnt(6)
	v_fmac_f32_e32 v4, v132, v140
	v_fmac_f32_e32 v4, v133, v141
	v_fmac_f32_e32 v4, v134, v142
	v_fmac_f32_e32 v4, v135, v143
	v_fmac_f32_e32 v4, v136, v144
	v_fmac_f32_e32 v4, v137, v145
	v_fmac_f32_e32 v4, v138, v146
	v_fmac_f32_e32 v4, v139, v147
	ds_read_b128 v[132:135], v148 offset:352
	ds_read_b128 v[136:139], v148 offset:368
	ds_read2_b32 v[140:141], v149 offset1:132
	ds_read2_b32 v[142:143], v150 offset0:8 offset1:140
	ds_read2_b32 v[144:145], v151 offset0:16 offset1:148
	ds_read2_b32 v[146:147], v152 offset0:24 offset1:156
	v_add_u32_e32 v149, 0x1080, v149
	v_add_u32_e32 v150, 0x1080, v150
	v_add_u32_e32 v151, 0x1080, v151
	v_add_u32_e32 v152, 0x1080, v152
	s_waitcnt lgkmcnt(6)
	v_fmac_f32_e32 v4, v116, v124
	v_fmac_f32_e32 v4, v117, v125
	v_fmac_f32_e32 v4, v118, v126
	v_fmac_f32_e32 v4, v119, v127
	v_fmac_f32_e32 v4, v120, v128
	v_fmac_f32_e32 v4, v121, v129
	v_fmac_f32_e32 v4, v122, v130
	v_fmac_f32_e32 v4, v123, v131
	ds_read_b128 v[116:119], v148 offset:384
	ds_read_b128 v[120:123], v148 offset:400
	ds_read2_b32 v[124:125], v149 offset1:132
	ds_read2_b32 v[126:127], v150 offset0:8 offset1:140
	ds_read2_b32 v[128:129], v151 offset0:16 offset1:148
	ds_read2_b32 v[130:131], v152 offset0:24 offset1:156
	v_add_u32_e32 v149, 0x1080, v149
	v_add_u32_e32 v150, 0x1080, v150
	v_add_u32_e32 v151, 0x1080, v151
	v_add_u32_e32 v152, 0x1080, v152
	s_waitcnt lgkmcnt(6)
	v_fmac_f32_e32 v4, v132, v140
	v_fmac_f32_e32 v4, v133, v141
	v_fmac_f32_e32 v4, v134, v142
	v_fmac_f32_e32 v4, v135, v143
	v_fmac_f32_e32 v4, v136, v144
	v_fmac_f32_e32 v4, v137, v145
	v_fmac_f32_e32 v4, v138, v146
	v_fmac_f32_e32 v4, v139, v147
	ds_read_b128 v[132:135], v148 offset:416
	ds_read_b128 v[136:139], v148 offset:432
	ds_read2_b32 v[140:141], v149 offset1:132
	ds_read2_b32 v[142:143], v150 offset0:8 offset1:140
	ds_read2_b32 v[144:145], v151 offset0:16 offset1:148
	ds_read2_b32 v[146:147], v152 offset0:24 offset1:156
	v_add_u32_e32 v149, 0x1080, v149
	v_add_u32_e32 v150, 0x1080, v150
	v_add_u32_e32 v151, 0x1080, v151
	v_add_u32_e32 v152, 0x1080, v152
	s_waitcnt lgkmcnt(6)
	v_fmac_f32_e32 v4, v116, v124
	v_fmac_f32_e32 v4, v117, v125
	v_fmac_f32_e32 v4, v118, v126
	v_fmac_f32_e32 v4, v119, v127
	v_fmac_f32_e32 v4, v120, v128
	v_fmac_f32_e32 v4, v121, v129
	v_fmac_f32_e32 v4, v122, v130
	v_fmac_f32_e32 v4, v123, v131
	ds_read_b128 v[116:119], v148 offset:448
	ds_read_b128 v[120:123], v148 offset:464
	ds_read2_b32 v[124:125], v149 offset1:132
	ds_read2_b32 v[126:127], v150 offset0:8 offset1:140
	ds_read2_b32 v[128:129], v151 offset0:16 offset1:148
	ds_read2_b32 v[130:131], v152 offset0:24 offset1:156
	v_add_u32_e32 v149, 0x1080, v149
	v_add_u32_e32 v150, 0x1080, v150
	v_add_u32_e32 v151, 0x1080, v151
	v_add_u32_e32 v152, 0x1080, v152
	s_waitcnt lgkmcnt(6)
	v_fmac_f32_e32 v4, v132, v140
	v_fmac_f32_e32 v4, v133, v141
	v_fmac_f32_e32 v4, v134, v142
	v_fmac_f32_e32 v4, v135, v143
	v_fmac_f32_e32 v4, v136, v144
	v_fmac_f32_e32 v4, v137, v145
	v_fmac_f32_e32 v4, v138, v146
	v_fmac_f32_e32 v4, v139, v147
	ds_read_b128 v[132:135], v148 offset:480
	ds_read_b128 v[136:139], v148 offset:496
	ds_read2_b32 v[140:141], v149 offset1:132
	ds_read2_b32 v[142:143], v150 offset0:8 offset1:140
	ds_read2_b32 v[144:145], v151 offset0:16 offset1:148
	ds_read2_b32 v[146:147], v152 offset0:24 offset1:156
	v_add_u32_e32 v149, 0x1080, v149
	v_add_u32_e32 v150, 0x1080, v150
	v_add_u32_e32 v151, 0x1080, v151
	v_add_u32_e32 v152, 0x1080, v152
	s_waitcnt lgkmcnt(6)
	v_fmac_f32_e32 v4, v116, v124
	v_fmac_f32_e32 v4, v117, v125
	v_fmac_f32_e32 v4, v118, v126
	v_fmac_f32_e32 v4, v119, v127
	v_fmac_f32_e32 v4, v120, v128
	v_fmac_f32_e32 v4, v121, v129
	v_fmac_f32_e32 v4, v122, v130
	v_fmac_f32_e32 v4, v123, v131
	ds_read_b32 v153, v148 offset:512
	ds_read_b32 v154, v149
	s_waitcnt lgkmcnt(2)
	v_fmac_f32_e32 v4, v132, v140
	v_fmac_f32_e32 v4, v133, v141
	v_fmac_f32_e32 v4, v134, v142
	v_fmac_f32_e32 v4, v135, v143
	v_fmac_f32_e32 v4, v136, v144
	v_fmac_f32_e32 v4, v137, v145
	v_fmac_f32_e32 v4, v138, v146
	v_fmac_f32_e32 v4, v139, v147
	s_waitcnt lgkmcnt(0)
	v_fmac_f32_e32 v4, v153, v154
